# phase 0: memory-prompt norm passes moved from blocks 0..63 to 192..255 (off the blocks with a 7th weight tile)
# baseline (speedup 1.0000x reference)
.LBB0_632:
	v_mov_b32_e32 v0, v147
	v_readlane_b32 s6, v243, 24
	v_ashrrev_i32_e32 v1, 6, v0
	s_cmpk_eq_u32 s28, 0x200
	s_cbranch_scc0 .Lmn_all
	s_sub_i32 s6, s6, 0x600
.Lmn_all:
	v_add_u32_e32 v16, s6, v1
	v_cmp_gt_u32_e32 vcc, s28, v16
	s_and_saveexec_b64 s[6:7], vcc
	s_cbranch_execz .LBB0_628
	v_and_b32_e32 v2, 64, v164
	v_add_u32_e32 v2, 64, v2
	v_xor_b32_e32 v3, 32, v164
	v_cmp_lt_i32_e32 vcc, v3, v2
	v_and_b32_e32 v1, 63, v0
	s_cmp_lg_u64 s[12:13], 0
	v_cndmask_b32_e32 v3, v164, v3, vcc
	v_lshlrev_b32_e32 v31, 2, v3
	v_xor_b32_e32 v3, 16, v164
	v_cmp_lt_i32_e32 vcc, v3, v2
	s_cselect_b64 s[10:11], -1, 0
	v_lshlrev_b32_e32 v136, 3, v1
	v_cndmask_b32_e32 v3, v164, v3, vcc
	v_lshlrev_b32_e32 v32, 2, v3
	v_xor_b32_e32 v3, 8, v164
	v_cmp_lt_i32_e32 vcc, v3, v2
	s_cmp_lg_u64 s[0:1], 0
	v_lshl_add_u64 v[18:19], s[12:13], 0, v[136:137]
	v_cndmask_b32_e32 v3, v164, v3, vcc
	v_lshlrev_b32_e32 v33, 2, v3
	v_xor_b32_e32 v3, 4, v164
	v_cmp_lt_i32_e32 vcc, v3, v2
	s_cselect_b64 s[12:13], -1, 0
	s_cmp_lg_u64 s[14:15], 0
	v_cndmask_b32_e32 v3, v164, v3, vcc
	v_lshlrev_b32_e32 v34, 2, v3
	v_xor_b32_e32 v3, 2, v164
	v_cmp_lt_i32_e32 vcc, v3, v2
	v_lshl_add_u64 v[20:21], s[14:15], 0, v[136:137]
	s_cselect_b64 s[14:15], -1, 0
	v_cndmask_b32_e32 v3, v164, v3, vcc
	v_lshlrev_b32_e32 v35, 2, v3
	v_xor_b32_e32 v3, 1, v164
	v_cmp_lt_i32_e32 vcc, v3, v2
	s_cmp_lg_u64 s[18:19], 0
	v_lshlrev_b32_e32 v0, 2, v1
	v_cndmask_b32_e32 v2, v164, v3, vcc
	v_lshlrev_b32_e32 v36, 2, v2
	v_lshlrev_b32_e32 v2, 4, v1
	v_mov_b32_e32 v3, v137
	v_lshl_add_u64 v[22:23], s[16:17], 0, v[2:3]
	s_cselect_b64 s[16:17], -1, 0
	s_cmp_lg_u64 s[24:25], 0
	s_mov_b64 s[8:9], 0
	v_cmp_eq_u32_e64 s[38:39], 0, v1
	v_lshl_add_u64 v[24:25], s[20:21], 0, v[2:3]
	v_lshl_add_u64 v[26:27], s[18:19], 0, v[136:137]
	s_cselect_b64 s[18:19], -1, 0
	v_lshl_add_u64 v[28:29], s[24:25], 0, v[2:3]
	s_sub_i32 s24, 0, s29
	v_lshlrev_b32_e32 v136, 2, v0
	s_and_b64 vcc, exec, s[12:13]
	s_cbranch_vccnz .Lnorm_pre_done
	global_load_dwordx4 v[60:63], v[22:23], off
	global_load_dwordx4 v[64:67], v[22:23], off offset:1024
	global_load_dwordx4 v[68:71], v[22:23], off offset:2048
	global_load_dwordx4 v[72:75], v[22:23], off offset:3072
	s_andn2_b64 vcc, exec, s[16:17]
	s_cbranch_vccnz .Lnorm_pre_done
	global_load_dwordx4 v[76:79], v[24:25], off
	global_load_dwordx4 v[80:83], v[24:25], off offset:1024
	global_load_dwordx4 v[84:87], v[24:25], off offset:2048
	global_load_dwordx4 v[88:91], v[24:25], off offset:3072
